# cache-policy: P0 bf16 weight stores marked nt (streaming writes)
# speedup vs baseline: 1.0020x; 1.0017x over previous
; #define LAS __attribute__((address_space(3)))
; __device__ __forceinline__ unsigned pk2(float lo, float hi) { return pg8::cvt_pk_bf16(lo, hi); }
; __device__ __forceinline__ void p0_transpose_item(const float* W, int K, int N, bfu* WT, int drow0, LAS float* scr, int k0, int n0, int lane, const float* gk) {
;     ...
; #pragma unroll
;     for (int j = 0; j < 4; ++j) { const int n = (lane >> 3) + 8 * j; const LAS float* s = scr + (8 * c) * 33 + n;
;         v4u o; o.x = pk2(s[0 * 33] * ga.x, s[1 * 33] * ga.y); o.y = pk2(s[2 * 33] * ga.z, s[3 * 33] * ga.w); o.z = pk2(s[4 * 33] * gb.x, s[5 * 33] * gb.y); o.w = pk2(s[6 * 33] * gb.z, s[7 * 33] * gb.w);
;         *(v4u*)(WT + (size_t)(drow0 + n) * K + k0 + 8 * c) = o; }
.LBB0_21:
	s_mul_hi_i32 s4, s22, 0x1900000
	s_mul_i32 s22, s22, 0x1900000
	s_add_u32 s25, s26, s22
	ds_read2_b32 v[18:19], v25 offset1:8
	ds_read2_b32 v[20:21], v25 offset0:33 offset1:41
	ds_read2_b32 v[56:57], v25 offset0:66 offset1:74
	ds_read2_b32 v[58:59], v25 offset0:99 offset1:107
	s_addc_u32 s4, s27, s4
	s_lshl_b64 s[22:23], s[28:29], 1
	s_add_u32 s22, s25, s22
	ds_read2_b32 v[60:61], v25 offset0:132 offset1:140
	ds_read2_b32 v[62:63], v25 offset0:165 offset1:173
	ds_read2_b32 v[64:65], v25 offset0:198 offset1:206
	ds_read2_b32 v[66:67], v25 offset0:231 offset1:239
	s_addc_u32 s23, s4, s23
	v_lshlrev_b32_e32 v10, 1, v8
	v_lshl_add_u64 v[14:15], s[22:23], 0, v[10:11]
	v_lshl_add_u64 v[54:55], v[14:15], 0, s[20:21]
	s_waitcnt lgkmcnt(7)
	v_mov_b32_e32 v14, v18
	s_waitcnt lgkmcnt(6)
	v_mov_b32_e32 v15, v20
	s_waitcnt lgkmcnt(5)
	v_mov_b32_e32 v16, v56
	s_waitcnt lgkmcnt(4)
	v_mov_b32_e32 v17, v58
	s_waitcnt vmcnt(0)
	v_pk_mul_f32 v[14:15], v[4:5], v[14:15]
	v_pk_mul_f32 v[16:17], v[6:7], v[16:17]
	v_cvt_pk_bf16_f32 v14, v14, v15
	v_cvt_pk_bf16_f32 v15, v16, v17
	s_waitcnt lgkmcnt(3)
	v_mov_b32_e32 v16, v60
	s_waitcnt lgkmcnt(2)
	v_mov_b32_e32 v17, v62
	s_waitcnt lgkmcnt(1)
	v_mov_b32_e32 v68, v64
	s_waitcnt lgkmcnt(0)
	v_mov_b32_e32 v69, v66
	v_pk_mul_f32 v[16:17], v[0:1], v[16:17]
	v_pk_mul_f32 v[68:69], v[2:3], v[68:69]
	v_cvt_pk_bf16_f32 v16, v16, v17
	v_cvt_pk_bf16_f32 v17, v68, v69
	v_or_b32_e32 v68, s24, v24
	v_ashrrev_i32_e32 v69, 31, v68
	v_lshlrev_b64 v[68:69], 12, v[68:69]
	v_lshl_add_u64 v[68:69], v[54:55], 0, v[68:69]
	v_mov_b32_e32 v20, v19
	v_mov_b32_e32 v58, v57
	global_store_dwordx4 v[68:69], v[14:17], off nt
	v_mov_b32_e32 v62, v61
	v_mov_b32_e32 v66, v65
	v_pk_mul_f32 v[14:15], v[4:5], v[20:21]
	v_pk_mul_f32 v[16:17], v[6:7], v[58:59]
	v_cvt_pk_bf16_f32 v14, v14, v15
	v_cvt_pk_bf16_f32 v15, v16, v17
	v_pk_mul_f32 v[16:17], v[0:1], v[62:63]
	v_pk_mul_f32 v[18:19], v[2:3], v[66:67]
	v_cvt_pk_bf16_f32 v16, v16, v17
	v_cvt_pk_bf16_f32 v17, v18, v19
	v_or_b32_e32 v18, s24, v26
	v_ashrrev_i32_e32 v19, 31, v18
	v_lshlrev_b64 v[18:19], 12, v[18:19]
	v_lshl_add_u64 v[18:19], v[54:55], 0, v[18:19]
	ds_read2_b32 v[20:21], v25 offset0:16 offset1:24
	ds_read2_b32 v[56:57], v25 offset0:49 offset1:57
	global_store_dwordx4 v[18:19], v[14:17], off nt
	ds_read2_b32 v[18:19], v25 offset0:82 offset1:90
	ds_read2_b32 v[58:59], v25 offset0:115 offset1:123
	ds_read2_b32 v[60:61], v25 offset0:148 offset1:156
	ds_read2_b32 v[62:63], v25 offset0:181 offset1:189
	ds_read2_b32 v[64:65], v25 offset0:214 offset1:222
	ds_read2_b32 v[66:67], v25 offset0:247 offset1:255
	s_waitcnt lgkmcnt(7)
	v_mov_b32_e32 v14, v20
	s_waitcnt lgkmcnt(6)
	v_mov_b32_e32 v15, v56
	s_waitcnt lgkmcnt(5)
	v_mov_b32_e32 v16, v18
	s_waitcnt lgkmcnt(4)
	v_mov_b32_e32 v17, v58
	v_pk_mul_f32 v[14:15], v[4:5], v[14:15]
	v_pk_mul_f32 v[16:17], v[6:7], v[16:17]
	v_cvt_pk_bf16_f32 v14, v14, v15
	v_cvt_pk_bf16_f32 v15, v16, v17
	s_waitcnt lgkmcnt(3)
	v_mov_b32_e32 v16, v60
	s_waitcnt lgkmcnt(2)
	v_mov_b32_e32 v17, v62
	v_mov_b32_e32 v56, v21
	v_mov_b32_e32 v58, v19
	v_mov_b32_e32 v62, v61
	v_pk_mul_f32 v[16:17], v[0:1], v[16:17]
	s_waitcnt lgkmcnt(1)
	v_mov_b32_e32 v68, v64
	s_waitcnt lgkmcnt(0)
	v_mov_b32_e32 v69, v66
	v_pk_mul_f32 v[4:5], v[4:5], v[56:57]
	v_pk_mul_f32 v[6:7], v[6:7], v[58:59]
	v_pk_mul_f32 v[0:1], v[0:1], v[62:63]
	v_mov_b32_e32 v66, v65
	v_pk_mul_f32 v[68:69], v[2:3], v[68:69]
	v_cvt_pk_bf16_f32 v4, v4, v5
	v_cvt_pk_bf16_f32 v5, v6, v7
	v_cvt_pk_bf16_f32 v6, v0, v1
	v_pk_mul_f32 v[0:1], v[2:3], v[66:67]
	v_cvt_pk_bf16_f32 v16, v16, v17
	v_cvt_pk_bf16_f32 v17, v68, v69
	v_or_b32_e32 v68, s24, v27
	v_cvt_pk_bf16_f32 v7, v0, v1
	v_or_b32_e32 v0, s24, v28
	v_ashrrev_i32_e32 v69, 31, v68
	v_ashrrev_i32_e32 v1, 31, v0
	v_lshlrev_b64 v[68:69], 12, v[68:69]
	v_lshlrev_b64 v[0:1], 12, v[0:1]
	v_lshl_add_u64 v[68:69], v[54:55], 0, v[68:69]
	v_lshl_add_u64 v[0:1], v[54:55], 0, v[0:1]
	global_store_dwordx4 v[68:69], v[14:17], off nt
	global_store_dwordx4 v[0:1], v[4:7], off nt
	s_waitcnt lgkmcnt(0)

; #define LDS_WAIT() asm volatile("s_waitcnt lgkmcnt(0)" ::: "memory")
; __device__ __forceinline__ void p0_transpose_item(const float* W, int K, int N, bfu* WT, int drow0, LAS float* scr, int k0, int n0, int lane, const float* gk) {
;     ...
;     for (int i = 0; i < 32; ++i) { const int kk = 2 * i + (lane >> 5); scr[kk * 33 + (lane & 31)] = __builtin_nontemporal_load(W + (size_t)(k0 + kk) * N + n0 + (lane & 31)); }
;     LDS_WAIT(); asm volatile("" ::: "memory");
.LBB0_28:
	v_lshl_add_u64 v[54:55], v[20:21], 0, s[26:27]
	v_lshl_add_u64 v[56:57], v[18:19], 0, s[26:27]
	v_lshl_add_u64 v[58:59], v[16:17], 0, s[26:27]
	v_lshl_add_u64 v[60:61], v[14:15], 0, s[26:27]
	v_lshl_add_u64 v[62:63], v[6:7], 0, s[26:27]
	v_lshl_add_u64 v[64:65], v[4:5], 0, s[26:27]
	v_lshl_add_u64 v[66:67], v[2:3], 0, s[26:27]
	v_lshl_add_u64 v[68:69], v[0:1], 0, s[26:27]
	global_load_dword v70, v[54:55], off nt
	global_load_dword v71, v[56:57], off nt
	global_load_dword v72, v[58:59], off nt
	global_load_dword v73, v[60:61], off nt
	global_load_dword v74, v[62:63], off nt
	global_load_dword v75, v[64:65], off nt
	global_load_dword v76, v[66:67], off nt
	global_load_dword v77, v[68:69], off nt
	s_add_u32 s26, s26, 0x20000
	s_addc_u32 s27, s27, 0
	v_lshl_add_u64 v[54:55], v[20:21], 0, s[26:27]
	v_lshl_add_u64 v[56:57], v[18:19], 0, s[26:27]
	v_lshl_add_u64 v[58:59], v[16:17], 0, s[26:27]
	v_lshl_add_u64 v[60:61], v[14:15], 0, s[26:27]
	v_lshl_add_u64 v[62:63], v[6:7], 0, s[26:27]
	v_lshl_add_u64 v[64:65], v[4:5], 0, s[26:27]
	v_lshl_add_u64 v[66:67], v[2:3], 0, s[26:27]
	v_lshl_add_u64 v[68:69], v[0:1], 0, s[26:27]
	global_load_dword v78, v[54:55], off nt
	global_load_dword v79, v[56:57], off nt
	global_load_dword v80, v[58:59], off nt
	global_load_dword v81, v[60:61], off nt
	global_load_dword v82, v[62:63], off nt
	global_load_dword v83, v[64:65], off nt
	global_load_dword v84, v[66:67], off nt
	global_load_dword v85, v[68:69], off nt
	s_add_u32 s26, s26, 0x20000
	s_addc_u32 s27, s27, 0
	v_lshl_add_u64 v[54:55], v[20:21], 0, s[26:27]
	v_lshl_add_u64 v[56:57], v[18:19], 0, s[26:27]
	v_lshl_add_u64 v[58:59], v[16:17], 0, s[26:27]
	v_lshl_add_u64 v[60:61], v[14:15], 0, s[26:27]
	v_lshl_add_u64 v[62:63], v[6:7], 0, s[26:27]
	v_lshl_add_u64 v[64:65], v[4:5], 0, s[26:27]
	v_lshl_add_u64 v[66:67], v[2:3], 0, s[26:27]
	v_lshl_add_u64 v[68:69], v[0:1], 0, s[26:27]
	global_load_dword v86, v[54:55], off nt
	global_load_dword v87, v[56:57], off nt
	global_load_dword v88, v[58:59], off nt
	global_load_dword v89, v[60:61], off nt
	global_load_dword v90, v[62:63], off nt
	global_load_dword v91, v[64:65], off nt
	global_load_dword v92, v[66:67], off nt
	global_load_dword v93, v[68:69], off nt
	s_add_u32 s26, s26, 0x20000
	s_addc_u32 s27, s27, 0
	v_lshl_add_u64 v[54:55], v[20:21], 0, s[26:27]
	v_lshl_add_u64 v[56:57], v[18:19], 0, s[26:27]
	v_lshl_add_u64 v[58:59], v[16:17], 0, s[26:27]
	v_lshl_add_u64 v[60:61], v[14:15], 0, s[26:27]
	v_lshl_add_u64 v[62:63], v[6:7], 0, s[26:27]
	v_lshl_add_u64 v[64:65], v[4:5], 0, s[26:27]
	v_lshl_add_u64 v[66:67], v[2:3], 0, s[26:27]
	v_lshl_add_u64 v[68:69], v[0:1], 0, s[26:27]
	global_load_dword v94, v[54:55], off nt
	global_load_dword v95, v[56:57], off nt
	global_load_dword v96, v[58:59], off nt
	global_load_dword v97, v[60:61], off nt
	global_load_dword v98, v[62:63], off nt
	global_load_dword v99, v[64:65], off nt
	global_load_dword v100, v[66:67], off nt
	global_load_dword v101, v[68:69], off nt
	s_add_u32 s26, s26, 0x20000
	s_addc_u32 s27, s27, 0
	v_add_u32_e32 v54, 0x400, v10
	s_waitcnt vmcnt(30)
	ds_write2_b32 v10, v70, v71 offset1:66
	s_waitcnt vmcnt(28)
	ds_write2_b32 v10, v72, v73 offset0:132 offset1:198
	s_waitcnt vmcnt(26)
	ds_write2_b32 v54, v74, v75 offset0:8 offset1:74
	s_waitcnt vmcnt(24)
	ds_write2_b32 v54, v76, v77 offset0:140 offset1:206
	v_add_u32_e32 v10, 0x840, v10
	v_add_u32_e32 v54, 0x400, v10
	s_waitcnt vmcnt(22)
	ds_write2_b32 v10, v78, v79 offset1:66
	s_waitcnt vmcnt(20)
	ds_write2_b32 v10, v80, v81 offset0:132 offset1:198
	s_waitcnt vmcnt(18)
; #define LAS __attribute__((address_space(3)))
; #define LDS_WAIT() asm volatile("s_waitcnt lgkmcnt(0)" ::: "memory")
; __device__ __forceinline__ unsigned pk2(float lo, float hi) { return pg8::cvt_pk_bf16(lo, hi); }
; __device__ __forceinline__ void p0_transpose_item(const float* W, int K, int N, bfu* WT, int drow0, LAS float* scr, int k0, int n0, int lane, const float* gk) {
;     ...
;     for (int i = 0; i < 32; ++i) { const int kk = 2 * i + (lane >> 5); scr[kk * 33 + (lane & 31)] = __builtin_nontemporal_load(W + (size_t)(k0 + kk) * N + n0 + (lane & 31)); }
;     LDS_WAIT(); asm volatile("" ::: "memory");
;     const int c = lane & 7;
;     f32x4 ga = (f32x4){1.f, 1.f, 1.f, 1.f}, gb = ga;
;     if (gk) { ga = *(const f32x4*)(gk + k0 + 8 * c); gb = *(const f32x4*)(gk + k0 + 8 * c + 4); }
; #pragma unroll
;     for (int j = 0; j < 4; ++j) { const int n = (lane >> 3) + 8 * j; const LAS float* s = scr + (8 * c) * 33 + n;
;         v4u o; o.x = pk2(s[0 * 33] * ga.x, s[1 * 33] * ga.y); o.y = pk2(s[2 * 33] * ga.z, s[3 * 33] * ga.w); o.z = pk2(s[4 * 33] * gb.x, s[5 * 33] * gb.y); o.w = pk2(s[6 * 33] * gb.z, s[7 * 33] * gb.w);
;         *(v4u*)(WT + (size_t)(drow0 + n) * K + k0 + 8 * c) = o; }
	ds_write2_b32 v54, v82, v83 offset0:8 offset1:74
	s_waitcnt vmcnt(16)
	ds_write2_b32 v54, v84, v85 offset0:140 offset1:206
	v_add_u32_e32 v10, 0x840, v10
	v_add_u32_e32 v54, 0x400, v10
	s_waitcnt vmcnt(14)
	ds_write2_b32 v10, v86, v87 offset1:66
	s_waitcnt vmcnt(12)
	ds_write2_b32 v10, v88, v89 offset0:132 offset1:198
	s_waitcnt vmcnt(10)
	ds_write2_b32 v54, v90, v91 offset0:8 offset1:74
	s_waitcnt vmcnt(8)
	ds_write2_b32 v54, v92, v93 offset0:140 offset1:206
	v_add_u32_e32 v10, 0x840, v10
	v_add_u32_e32 v54, 0x400, v10
	s_waitcnt vmcnt(6)
	ds_write2_b32 v10, v94, v95 offset1:66
	s_waitcnt vmcnt(4)
	ds_write2_b32 v10, v96, v97 offset0:132 offset1:198
	s_waitcnt vmcnt(2)
	ds_write2_b32 v54, v98, v99 offset0:8 offset1:74
	s_waitcnt vmcnt(0)
	ds_write2_b32 v54, v100, v101 offset0:140 offset1:206
	v_add_u32_e32 v10, 0x840, v10
	s_and_b32 s4, s30, 0x7fffffc0
	s_lshl_b32 s27, s38, 5
	s_addk_i32 s4, 0xb300
	s_mul_i32 s26, s22, 0x1600000
	s_and_b32 s27, s27, 0x7e0
	s_mul_hi_i32 s23, s22, 0x1600000
	s_add_u32 s26, s24, s26
	s_addc_u32 s23, s25, s23
	s_waitcnt lgkmcnt(0)
	s_lshl_b64 s[24:25], s[4:5], 1
	s_add_u32 s24, s26, s24
	s_addc_u32 s25, s23, s25
	v_lshlrev_b32_e32 v10, 1, v8
	ds_read2_b32 v[4:5], v25 offset0:33 offset1:41
	ds_read2_b32 v[6:7], v25 offset1:8
	ds_read2_b32 v[14:15], v25 offset0:66 offset1:74
	ds_read2_b32 v[16:17], v25 offset0:99 offset1:107
	ds_read2_b32 v[18:19], v25 offset0:132 offset1:140
	ds_read2_b32 v[20:21], v25 offset0:165 offset1:173
	ds_read2_b32 v[54:55], v25 offset0:198 offset1:206
	ds_read2_b32 v[56:57], v25 offset0:231 offset1:239
	v_lshl_add_u64 v[0:1], s[24:25], 0, v[10:11]
	v_lshl_add_u64 v[58:59], v[0:1], 0, s[6:7]
	s_waitcnt lgkmcnt(6)
	v_cvt_pk_bf16_f32 v0, v6, v4
	v_or_b32_e32 v4, s27, v24
	v_mul_u32_u24_e32 v4, 0x1600, v4
	v_lshlrev_b32_e32 v10, 1, v4
	s_waitcnt lgkmcnt(4)
	v_cvt_pk_bf16_f32 v1, v14, v16
	s_waitcnt lgkmcnt(2)
	v_cvt_pk_bf16_f32 v2, v18, v20
	s_waitcnt lgkmcnt(0)
	v_cvt_pk_bf16_f32 v3, v54, v56
	v_lshl_add_u64 v[60:61], v[58:59], 0, v[10:11]
	v_or_b32_e32 v4, s27, v26
	global_store_dwordx4 v[60:61], v[0:3], off nt
	v_mul_u32_u24_e32 v4, 0x1600, v4
	v_lshlrev_b32_e32 v10, 1, v4
	v_cvt_pk_bf16_f32 v0, v7, v5
	v_cvt_pk_bf16_f32 v1, v15, v17
	v_cvt_pk_bf16_f32 v2, v19, v21
	v_cvt_pk_bf16_f32 v3, v55, v57
	ds_read2_b32 v[6:7], v25 offset0:16 offset1:24
	ds_read2_b32 v[14:15], v25 offset0:49 offset1:57
	ds_read2_b32 v[16:17], v25 offset0:82 offset1:90
	ds_read2_b32 v[18:19], v25 offset0:115 offset1:123
	ds_read2_b32 v[20:21], v25 offset0:148 offset1:156
	ds_read2_b32 v[54:55], v25 offset0:181 offset1:189
	ds_read2_b32 v[56:57], v25 offset0:214 offset1:222
	ds_read2_b32 v[60:61], v25 offset0:247 offset1:255
	v_lshl_add_u64 v[4:5], v[58:59], 0, v[10:11]
	global_store_dwordx4 v[4:5], v[0:3], off nt
	v_or_b32_e32 v4, s27, v27
	v_mul_u32_u24_e32 v4, 0x1600, v4
	v_lshlrev_b32_e32 v10, 1, v4
	s_waitcnt lgkmcnt(6)
	v_cvt_pk_bf16_f32 v0, v6, v14
	s_waitcnt lgkmcnt(4)
	v_cvt_pk_bf16_f32 v1, v16, v18
	s_waitcnt lgkmcnt(2)
	v_cvt_pk_bf16_f32 v2, v20, v54
	s_waitcnt lgkmcnt(0)
	v_cvt_pk_bf16_f32 v3, v56, v60
	v_lshl_add_u64 v[4:5], v[58:59], 0, v[10:11]
	global_store_dwordx4 v[4:5], v[0:3], off nt
	v_or_b32_e32 v4, s27, v28
	v_mul_u32_u24_e32 v4, 0x1600, v4
	v_lshlrev_b32_e32 v10, 1, v4
	v_cvt_pk_bf16_f32 v0, v7, v15
	v_cvt_pk_bf16_f32 v1, v17, v19
	v_cvt_pk_bf16_f32 v2, v21, v55
	v_cvt_pk_bf16_f32 v3, v57, v61
	v_lshl_add_u64 v[4:5], v[58:59], 0, v[10:11]
	global_store_dwordx4 v[4:5], v[0:3], off nt
	s_waitcnt lgkmcnt(0)
	s_mov_b64 s[24:25], 0

; #define LAS __attribute__((address_space(3)))
; __device__ __forceinline__ unsigned pk2(float lo, float hi) { return pg8::cvt_pk_bf16(lo, hi); }
; __device__ __forceinline__ void p0_transpose_item(const float* W, int K, int N, bfu* WT, int drow0, LAS float* scr, int k0, int n0, int lane, const float* gk) {
;     ...
; #pragma unroll
;     for (int j = 0; j < 4; ++j) { const int n = (lane >> 3) + 8 * j; const LAS float* s = scr + (8 * c) * 33 + n;
;         v4u o; o.x = pk2(s[0 * 33] * ga.x, s[1 * 33] * ga.y); o.y = pk2(s[2 * 33] * ga.z, s[3 * 33] * ga.w); o.z = pk2(s[4 * 33] * gb.x, s[5 * 33] * gb.y); o.w = pk2(s[6 * 33] * gb.z, s[7 * 33] * gb.w);
;         *(v4u*)(WT + (size_t)(drow0 + n) * K + k0 + 8 * c) = o; }
.LBB0_36:
	s_lshl_b32 s23, s23, 6
	s_and_b32 s23, s23, 0x3f00
	s_and_b32 s4, s4, 0x60
	s_or_b32 s4, s4, s23
	s_add_u32 s23, s24, s35
	ds_read2_b32 v[18:19], v25 offset1:8
	ds_read2_b32 v[20:21], v25 offset0:33 offset1:41
	ds_read2_b32 v[56:57], v25 offset0:66 offset1:74
	ds_read2_b32 v[58:59], v25 offset0:99 offset1:107
	s_addc_u32 s25, s25, s34
	s_bitset1_b32 s4, 7
	s_lshl_b32 s24, s28, 1
	s_add_u32 s24, s23, s24
	ds_read2_b32 v[60:61], v25 offset0:132 offset1:140
	ds_read2_b32 v[62:63], v25 offset0:165 offset1:173
	ds_read2_b32 v[64:65], v25 offset0:198 offset1:206
	ds_read2_b32 v[66:67], v25 offset0:231 offset1:239
	s_addc_u32 s25, s25, 0
	v_lshlrev_b32_e32 v10, 1, v8
	v_lshl_add_u64 v[14:15], s[24:25], 0, v[10:11]
	v_lshl_add_u64 v[54:55], v[14:15], 0, s[16:17]
	s_waitcnt lgkmcnt(7)
	v_mov_b32_e32 v14, v18
	s_waitcnt lgkmcnt(6)
	v_mov_b32_e32 v15, v20
	s_waitcnt lgkmcnt(5)
	v_mov_b32_e32 v16, v56
	s_waitcnt lgkmcnt(4)
	v_mov_b32_e32 v17, v58
	s_waitcnt vmcnt(0)
	v_pk_mul_f32 v[14:15], v[4:5], v[14:15]
	v_pk_mul_f32 v[16:17], v[6:7], v[16:17]
	v_cvt_pk_bf16_f32 v14, v14, v15
	v_cvt_pk_bf16_f32 v15, v16, v17
	s_waitcnt lgkmcnt(3)
	v_mov_b32_e32 v16, v60
	s_waitcnt lgkmcnt(2)
	v_mov_b32_e32 v17, v62
	s_waitcnt lgkmcnt(1)
	v_mov_b32_e32 v68, v64
	s_waitcnt lgkmcnt(0)
	v_mov_b32_e32 v69, v66
	v_or_b32_e32 v10, s4, v24
	v_pk_mul_f32 v[16:17], v[0:1], v[16:17]
	v_pk_mul_f32 v[68:69], v[2:3], v[68:69]
	v_lshlrev_b32_e32 v10, 12, v10
	v_cvt_pk_bf16_f32 v16, v16, v17
	v_cvt_pk_bf16_f32 v17, v68, v69
	v_lshl_add_u64 v[68:69], v[54:55], 0, v[10:11]
	v_mov_b32_e32 v20, v19
	v_mov_b32_e32 v58, v57
	global_store_dwordx4 v[68:69], v[14:17], off nt
	v_mov_b32_e32 v62, v61
	v_mov_b32_e32 v66, v65
	v_pk_mul_f32 v[14:15], v[4:5], v[20:21]
	v_pk_mul_f32 v[16:17], v[6:7], v[58:59]
	v_or_b32_e32 v10, s4, v26
	v_cvt_pk_bf16_f32 v14, v14, v15
	v_cvt_pk_bf16_f32 v15, v16, v17
	v_pk_mul_f32 v[16:17], v[0:1], v[62:63]
	v_pk_mul_f32 v[18:19], v[2:3], v[66:67]
	v_lshlrev_b32_e32 v10, 12, v10
	v_cvt_pk_bf16_f32 v16, v16, v17
	v_cvt_pk_bf16_f32 v17, v18, v19
	v_lshl_add_u64 v[56:57], v[54:55], 0, v[10:11]
	ds_read2_b32 v[18:19], v25 offset0:16 offset1:24
	ds_read2_b32 v[20:21], v25 offset0:49 offset1:57
	global_store_dwordx4 v[56:57], v[14:17], off nt
	ds_read2_b32 v[56:57], v25 offset0:82 offset1:90
	ds_read2_b32 v[58:59], v25 offset0:115 offset1:123
	ds_read2_b32 v[60:61], v25 offset0:148 offset1:156
	ds_read2_b32 v[62:63], v25 offset0:181 offset1:189
	ds_read2_b32 v[64:65], v25 offset0:214 offset1:222
	ds_read2_b32 v[66:67], v25 offset0:247 offset1:255
	s_waitcnt lgkmcnt(7)
	v_mov_b32_e32 v14, v18
	s_waitcnt lgkmcnt(6)
	v_mov_b32_e32 v15, v20
	s_waitcnt lgkmcnt(5)
	v_mov_b32_e32 v16, v56
	s_waitcnt lgkmcnt(4)
	v_mov_b32_e32 v17, v58
	v_pk_mul_f32 v[14:15], v[4:5], v[14:15]
	v_pk_mul_f32 v[16:17], v[6:7], v[16:17]
	v_cvt_pk_bf16_f32 v14, v14, v15
	v_cvt_pk_bf16_f32 v15, v16, v17
	s_waitcnt lgkmcnt(3)
	v_mov_b32_e32 v16, v60
	s_waitcnt lgkmcnt(2)
	v_mov_b32_e32 v17, v62
	v_mov_b32_e32 v20, v19
	v_mov_b32_e32 v58, v57
	v_mov_b32_e32 v62, v61
	v_pk_mul_f32 v[16:17], v[0:1], v[16:17]
	s_waitcnt lgkmcnt(0)
	v_mov_b32_e32 v69, v66
	v_pk_mul_f32 v[4:5], v[4:5], v[20:21]
	v_pk_mul_f32 v[6:7], v[6:7], v[58:59]
	v_pk_mul_f32 v[0:1], v[0:1], v[62:63]
	v_mov_b32_e32 v66, v65
	v_mov_b32_e32 v68, v64
	v_or_b32_e32 v10, s4, v27
	v_cvt_pk_bf16_f32 v4, v4, v5
	v_cvt_pk_bf16_f32 v5, v6, v7
	v_cvt_pk_bf16_f32 v6, v0, v1
	v_pk_mul_f32 v[0:1], v[2:3], v[66:67]
	v_pk_mul_f32 v[68:69], v[2:3], v[68:69]
	v_lshlrev_b32_e32 v10, 12, v10
	v_cvt_pk_bf16_f32 v7, v0, v1
	v_or_b32_e32 v0, s4, v28
	v_cvt_pk_bf16_f32 v16, v16, v17
	v_cvt_pk_bf16_f32 v17, v68, v69
	v_lshl_add_u64 v[68:69], v[54:55], 0, v[10:11]
	v_lshlrev_b32_e32 v10, 12, v0
	v_lshl_add_u64 v[0:1], v[54:55], 0, v[10:11]
	global_store_dwordx4 v[68:69], v[14:17], off nt
	global_store_dwordx4 v[0:1], v[4:7], off nt
	s_waitcnt lgkmcnt(0)

; #define LAS __attribute__((address_space(3)))
; __device__ __forceinline__ unsigned pk2(float lo, float hi) { return pg8::cvt_pk_bf16(lo, hi); }
; __device__ __forceinline__ void p0_transpose_item(const float* W, int K, int N, bfu* WT, int drow0, LAS float* scr, int k0, int n0, int lane, const float* gk) {
;     ...
; #pragma unroll
;     for (int j = 0; j < 4; ++j) { const int n = (lane >> 3) + 8 * j; const LAS float* s = scr + (8 * c) * 33 + n;
;         v4u o; o.x = pk2(s[0 * 33] * ga.x, s[1 * 33] * ga.y); o.y = pk2(s[2 * 33] * ga.z, s[3 * 33] * ga.w); o.z = pk2(s[4 * 33] * gb.x, s[5 * 33] * gb.y); o.w = pk2(s[6 * 33] * gb.z, s[7 * 33] * gb.w);
;         *(v4u*)(WT + (size_t)(drow0 + n) * K + k0 + 8 * c) = o; }
.LBB0_44:
	s_lshl_b32 s4, s4, 6
	s_and_b32 s23, s23, 0x60
	s_add_u32 s24, s24, s35
	s_addc_u32 s25, s25, s34
	s_and_b32 s4, s4, 0x3f00
	ds_read2_b32 v[18:19], v25 offset1:8
	ds_read2_b32 v[20:21], v25 offset0:33 offset1:41
	ds_read2_b32 v[56:57], v25 offset0:66 offset1:74
	ds_read2_b32 v[58:59], v25 offset0:99 offset1:107
	s_or_b32 s4, s4, s23
	s_lshl_b32 s23, s28, 1
	s_add_u32 s24, s24, s23
	ds_read2_b32 v[60:61], v25 offset0:132 offset1:140
	ds_read2_b32 v[62:63], v25 offset0:165 offset1:173
	ds_read2_b32 v[64:65], v25 offset0:198 offset1:206
	ds_read2_b32 v[66:67], v25 offset0:231 offset1:239
	s_addc_u32 s25, s25, 0
	v_lshlrev_b32_e32 v10, 1, v8
	v_lshl_add_u64 v[14:15], s[24:25], 0, v[10:11]
	v_lshl_add_u64 v[54:55], v[14:15], 0, s[16:17]
	s_waitcnt lgkmcnt(7)
	v_mov_b32_e32 v14, v18
	s_waitcnt lgkmcnt(6)
	v_mov_b32_e32 v15, v20
	s_waitcnt lgkmcnt(5)
	v_mov_b32_e32 v16, v56
	s_waitcnt lgkmcnt(4)
	v_mov_b32_e32 v17, v58
	s_waitcnt vmcnt(0)
	v_pk_mul_f32 v[14:15], v[4:5], v[14:15]
	v_pk_mul_f32 v[16:17], v[6:7], v[16:17]
	v_cvt_pk_bf16_f32 v14, v14, v15
	v_cvt_pk_bf16_f32 v15, v16, v17
	s_waitcnt lgkmcnt(3)
	v_mov_b32_e32 v16, v60
	s_waitcnt lgkmcnt(2)
	v_mov_b32_e32 v17, v62
	s_waitcnt lgkmcnt(1)
	v_mov_b32_e32 v68, v64
	s_waitcnt lgkmcnt(0)
	v_mov_b32_e32 v69, v66
	v_or_b32_e32 v10, s4, v24
	v_pk_mul_f32 v[16:17], v[0:1], v[16:17]
	v_pk_mul_f32 v[68:69], v[2:3], v[68:69]
	v_lshlrev_b32_e32 v10, 12, v10
	v_cvt_pk_bf16_f32 v16, v16, v17
	v_cvt_pk_bf16_f32 v17, v68, v69
	v_lshl_add_u64 v[68:69], v[54:55], 0, v[10:11]
	v_mov_b32_e32 v20, v19
	v_mov_b32_e32 v58, v57
	global_store_dwordx4 v[68:69], v[14:17], off nt
	v_mov_b32_e32 v62, v61
	v_mov_b32_e32 v66, v65
	v_pk_mul_f32 v[14:15], v[4:5], v[20:21]
	v_pk_mul_f32 v[16:17], v[6:7], v[58:59]
	v_or_b32_e32 v10, s4, v26
	v_cvt_pk_bf16_f32 v14, v14, v15
	v_cvt_pk_bf16_f32 v15, v16, v17
	v_pk_mul_f32 v[16:17], v[0:1], v[62:63]
	v_pk_mul_f32 v[18:19], v[2:3], v[66:67]
	v_lshlrev_b32_e32 v10, 12, v10
	v_cvt_pk_bf16_f32 v16, v16, v17
	v_cvt_pk_bf16_f32 v17, v18, v19
	v_lshl_add_u64 v[56:57], v[54:55], 0, v[10:11]
	ds_read2_b32 v[18:19], v25 offset0:16 offset1:24
	ds_read2_b32 v[20:21], v25 offset0:49 offset1:57
	global_store_dwordx4 v[56:57], v[14:17], off nt
	ds_read2_b32 v[56:57], v25 offset0:82 offset1:90
	ds_read2_b32 v[58:59], v25 offset0:115 offset1:123
	ds_read2_b32 v[60:61], v25 offset0:148 offset1:156
	ds_read2_b32 v[62:63], v25 offset0:181 offset1:189
	ds_read2_b32 v[64:65], v25 offset0:214 offset1:222
	ds_read2_b32 v[66:67], v25 offset0:247 offset1:255
	s_waitcnt lgkmcnt(7)
	v_mov_b32_e32 v14, v18
	s_waitcnt lgkmcnt(6)
	v_mov_b32_e32 v15, v20
	s_waitcnt lgkmcnt(5)
	v_mov_b32_e32 v16, v56
	s_waitcnt lgkmcnt(4)
	v_mov_b32_e32 v17, v58
	v_pk_mul_f32 v[14:15], v[4:5], v[14:15]
	v_pk_mul_f32 v[16:17], v[6:7], v[16:17]
	v_cvt_pk_bf16_f32 v14, v14, v15
	v_cvt_pk_bf16_f32 v15, v16, v17
	s_waitcnt lgkmcnt(3)
	v_mov_b32_e32 v16, v60
	s_waitcnt lgkmcnt(2)
	v_mov_b32_e32 v17, v62
	v_mov_b32_e32 v20, v19
	v_mov_b32_e32 v58, v57
	v_mov_b32_e32 v62, v61
	v_pk_mul_f32 v[16:17], v[0:1], v[16:17]
	s_waitcnt lgkmcnt(0)
	v_mov_b32_e32 v69, v66
	v_pk_mul_f32 v[4:5], v[4:5], v[20:21]
	v_pk_mul_f32 v[6:7], v[6:7], v[58:59]
	v_pk_mul_f32 v[0:1], v[0:1], v[62:63]
	v_mov_b32_e32 v66, v65
	v_mov_b32_e32 v68, v64
	v_or_b32_e32 v10, s4, v27
	v_cvt_pk_bf16_f32 v4, v4, v5
	v_cvt_pk_bf16_f32 v5, v6, v7
	v_cvt_pk_bf16_f32 v6, v0, v1
	v_pk_mul_f32 v[0:1], v[2:3], v[66:67]
	v_pk_mul_f32 v[68:69], v[2:3], v[68:69]
	v_lshlrev_b32_e32 v10, 12, v10
	v_cvt_pk_bf16_f32 v7, v0, v1
	v_or_b32_e32 v0, s4, v28
	v_cvt_pk_bf16_f32 v16, v16, v17
	v_cvt_pk_bf16_f32 v17, v68, v69
	v_lshl_add_u64 v[68:69], v[54:55], 0, v[10:11]
	v_lshlrev_b32_e32 v10, 12, v0
	v_lshl_add_u64 v[0:1], v[54:55], 0, v[10:11]
	global_store_dwordx4 v[68:69], v[14:17], off nt
	global_store_dwordx4 v[0:1], v[4:7], off nt
	s_waitcnt lgkmcnt(0)

; #define LAS __attribute__((address_space(3)))
; #define LDS_WAIT() asm volatile("s_waitcnt lgkmcnt(0)" ::: "memory")
; __device__ __forceinline__ unsigned pk2(float lo, float hi) { return pg8::cvt_pk_bf16(lo, hi); }
; __device__ __forceinline__ void p0_transpose_item(const float* W, int K, int N, bfu* WT, int drow0, LAS float* scr, int k0, int n0, int lane, const float* gk) {
; #pragma unroll 8
;     for (int i = 0; i < 32; ++i) { const int kk = 2 * i + (lane >> 5); scr[kk * 33 + (lane & 31)] = __builtin_nontemporal_load(W + (size_t)(k0 + kk) * N + n0 + (lane & 31)); }
;     LDS_WAIT(); asm volatile("" ::: "memory");
;     const int c = lane & 7;
;     f32x4 ga = (f32x4){1.f, 1.f, 1.f, 1.f}, gb = ga;
;     if (gk) { ga = *(const f32x4*)(gk + k0 + 8 * c); gb = *(const f32x4*)(gk + k0 + 8 * c + 4); }
; #pragma unroll
;     for (int j = 0; j < 4; ++j) { const int n = (lane >> 3) + 8 * j; const LAS float* s = scr + (8 * c) * 33 + n;
;         v4u o; o.x = pk2(s[0 * 33] * ga.x, s[1 * 33] * ga.y); o.y = pk2(s[2 * 33] * ga.z, s[3 * 33] * ga.w); o.z = pk2(s[4 * 33] * gb.x, s[5 * 33] * gb.y); o.w = pk2(s[6 * 33] * gb.z, s[7 * 33] * gb.w);
;         *(v4u*)(WT + (size_t)(drow0 + n) * K + k0 + 8 * c) = o; }
;     LDS_WAIT(); asm volatile("" ::: "memory");
.LBB0_48:
	v_lshl_add_u64 v[54:55], v[20:21], 0, s[26:27]
	v_lshl_add_u64 v[56:57], v[18:19], 0, s[26:27]
	v_lshl_add_u64 v[58:59], v[16:17], 0, s[26:27]
	v_lshl_add_u64 v[60:61], v[14:15], 0, s[26:27]
	v_lshl_add_u64 v[62:63], v[6:7], 0, s[26:27]
	v_lshl_add_u64 v[64:65], v[4:5], 0, s[26:27]
	v_lshl_add_u64 v[66:67], v[2:3], 0, s[26:27]
	v_lshl_add_u64 v[68:69], v[0:1], 0, s[26:27]
	global_load_dword v70, v[54:55], off nt
	global_load_dword v71, v[56:57], off nt
	global_load_dword v72, v[58:59], off nt
	global_load_dword v73, v[60:61], off nt
	global_load_dword v74, v[62:63], off nt
	global_load_dword v75, v[64:65], off nt
	global_load_dword v76, v[66:67], off nt
	global_load_dword v77, v[68:69], off nt
	s_add_u32 s26, s26, 0x20000
	s_addc_u32 s27, s27, 0
	v_lshl_add_u64 v[54:55], v[20:21], 0, s[26:27]
	v_lshl_add_u64 v[56:57], v[18:19], 0, s[26:27]
	v_lshl_add_u64 v[58:59], v[16:17], 0, s[26:27]
	v_lshl_add_u64 v[60:61], v[14:15], 0, s[26:27]
	v_lshl_add_u64 v[62:63], v[6:7], 0, s[26:27]
	v_lshl_add_u64 v[64:65], v[4:5], 0, s[26:27]
	v_lshl_add_u64 v[66:67], v[2:3], 0, s[26:27]
	v_lshl_add_u64 v[68:69], v[0:1], 0, s[26:27]
	global_load_dword v78, v[54:55], off nt
	global_load_dword v79, v[56:57], off nt
	global_load_dword v80, v[58:59], off nt
	global_load_dword v81, v[60:61], off nt
	global_load_dword v82, v[62:63], off nt
	global_load_dword v83, v[64:65], off nt
	global_load_dword v84, v[66:67], off nt
	global_load_dword v85, v[68:69], off nt
	s_add_u32 s26, s26, 0x20000
	s_addc_u32 s27, s27, 0
	v_lshl_add_u64 v[54:55], v[20:21], 0, s[26:27]
	v_lshl_add_u64 v[56:57], v[18:19], 0, s[26:27]
	v_lshl_add_u64 v[58:59], v[16:17], 0, s[26:27]
	v_lshl_add_u64 v[60:61], v[14:15], 0, s[26:27]
	v_lshl_add_u64 v[62:63], v[6:7], 0, s[26:27]
	v_lshl_add_u64 v[64:65], v[4:5], 0, s[26:27]
	v_lshl_add_u64 v[66:67], v[2:3], 0, s[26:27]
	v_lshl_add_u64 v[68:69], v[0:1], 0, s[26:27]
	global_load_dword v86, v[54:55], off nt
	global_load_dword v87, v[56:57], off nt
	global_load_dword v88, v[58:59], off nt
	global_load_dword v89, v[60:61], off nt
	global_load_dword v90, v[62:63], off nt
	global_load_dword v91, v[64:65], off nt
	global_load_dword v92, v[66:67], off nt
	global_load_dword v93, v[68:69], off nt
	s_add_u32 s26, s26, 0x20000
	s_addc_u32 s27, s27, 0
	v_lshl_add_u64 v[54:55], v[20:21], 0, s[26:27]
	v_lshl_add_u64 v[56:57], v[18:19], 0, s[26:27]
	v_lshl_add_u64 v[58:59], v[16:17], 0, s[26:27]
	v_lshl_add_u64 v[60:61], v[14:15], 0, s[26:27]
	v_lshl_add_u64 v[62:63], v[6:7], 0, s[26:27]
	v_lshl_add_u64 v[64:65], v[4:5], 0, s[26:27]
	v_lshl_add_u64 v[66:67], v[2:3], 0, s[26:27]
	v_lshl_add_u64 v[68:69], v[0:1], 0, s[26:27]
	global_load_dword v94, v[54:55], off nt
	global_load_dword v95, v[56:57], off nt
	global_load_dword v96, v[58:59], off nt
	global_load_dword v97, v[60:61], off nt
	global_load_dword v98, v[62:63], off nt
	global_load_dword v99, v[64:65], off nt
	global_load_dword v100, v[66:67], off nt
	global_load_dword v101, v[68:69], off nt
	s_add_u32 s26, s26, 0x20000
	s_addc_u32 s27, s27, 0
	v_add_u32_e32 v54, 0x400, v10
	s_waitcnt vmcnt(30)
	ds_write2_b32 v10, v70, v71 offset1:66
	s_waitcnt vmcnt(28)
	ds_write2_b32 v10, v72, v73 offset0:132 offset1:198
	s_waitcnt vmcnt(26)
	ds_write2_b32 v54, v74, v75 offset0:8 offset1:74
	s_waitcnt vmcnt(24)
	ds_write2_b32 v54, v76, v77 offset0:140 offset1:206
	v_add_u32_e32 v10, 0x840, v10
	v_add_u32_e32 v54, 0x400, v10
	s_waitcnt vmcnt(22)
	ds_write2_b32 v10, v78, v79 offset1:66
	s_waitcnt vmcnt(20)
	ds_write2_b32 v10, v80, v81 offset0:132 offset1:198
	s_waitcnt vmcnt(18)
	ds_write2_b32 v54, v82, v83 offset0:8 offset1:74
	s_waitcnt vmcnt(16)
	ds_write2_b32 v54, v84, v85 offset0:140 offset1:206
	v_add_u32_e32 v10, 0x840, v10
	v_add_u32_e32 v54, 0x400, v10
	s_waitcnt vmcnt(14)
	ds_write2_b32 v10, v86, v87 offset1:66
	s_waitcnt vmcnt(12)
	ds_write2_b32 v10, v88, v89 offset0:132 offset1:198
	s_waitcnt vmcnt(10)
	ds_write2_b32 v54, v90, v91 offset0:8 offset1:74
	s_waitcnt vmcnt(8)
	ds_write2_b32 v54, v92, v93 offset0:140 offset1:206
	v_add_u32_e32 v10, 0x840, v10
	v_add_u32_e32 v54, 0x400, v10
	s_waitcnt vmcnt(6)
	ds_write2_b32 v10, v94, v95 offset1:66
	s_waitcnt vmcnt(4)
	ds_write2_b32 v10, v96, v97 offset0:132 offset1:198
	s_waitcnt vmcnt(2)
	ds_write2_b32 v54, v98, v99 offset0:8 offset1:74
	s_waitcnt vmcnt(0)
	ds_write2_b32 v54, v100, v101 offset0:140 offset1:206
	v_add_u32_e32 v10, 0x840, v10
	s_and_b32 s4, s30, 0x3fc0
	s_lshl_b32 s26, s38, 5
	s_addk_i32 s4, 0xe700
	s_and_b32 s28, s26, 0x7e0
	s_lshl_b64 s[26:27], s[22:23], 23
	s_add_u32 s23, s24, s26
	s_waitcnt lgkmcnt(0)
	s_addc_u32 s26, s25, s27
	s_lshl_b64 s[24:25], s[4:5], 1
	s_add_u32 s24, s23, s24
	ds_read2_b32 v[4:5], v25 offset0:33 offset1:41
	ds_read2_b32 v[6:7], v25 offset1:8
	ds_read2_b32 v[14:15], v25 offset0:66 offset1:74
	ds_read2_b32 v[16:17], v25 offset0:99 offset1:107
	ds_read2_b32 v[18:19], v25 offset0:132 offset1:140
	ds_read2_b32 v[20:21], v25 offset0:165 offset1:173
	ds_read2_b32 v[54:55], v25 offset0:198 offset1:206
	ds_read2_b32 v[56:57], v25 offset0:231 offset1:239
	s_addc_u32 s25, s26, s25
	v_lshlrev_b32_e32 v10, 1, v8
	v_lshl_add_u64 v[0:1], s[24:25], 0, v[10:11]
	v_lshl_add_u64 v[58:59], v[0:1], 0, s[18:19]
	s_waitcnt lgkmcnt(6)
	v_cvt_pk_bf16_f32 v0, v6, v4
	v_or_b32_e32 v4, s28, v24
	v_lshlrev_b32_e32 v10, 12, v4
	s_waitcnt lgkmcnt(4)
	v_cvt_pk_bf16_f32 v1, v14, v16
	s_waitcnt lgkmcnt(2)
	v_cvt_pk_bf16_f32 v2, v18, v20
	s_waitcnt lgkmcnt(0)
	v_cvt_pk_bf16_f32 v3, v54, v56
	v_lshl_add_u64 v[60:61], v[58:59], 0, v[10:11]
	global_store_dwordx4 v[60:61], v[0:3], off nt
	v_or_b32_e32 v4, s28, v26
	v_lshlrev_b32_e32 v10, 12, v4
	v_cvt_pk_bf16_f32 v0, v7, v5
	v_cvt_pk_bf16_f32 v1, v15, v17
	v_cvt_pk_bf16_f32 v2, v19, v21
	v_cvt_pk_bf16_f32 v3, v55, v57
	ds_read2_b32 v[6:7], v25 offset0:49 offset1:57
	ds_read2_b32 v[14:15], v25 offset0:16 offset1:24
	ds_read2_b32 v[16:17], v25 offset0:82 offset1:90
	ds_read2_b32 v[18:19], v25 offset0:115 offset1:123
	ds_read2_b32 v[20:21], v25 offset0:148 offset1:156
	ds_read2_b32 v[54:55], v25 offset0:181 offset1:189
	ds_read2_b32 v[56:57], v25 offset0:214 offset1:222
	ds_read2_b32 v[60:61], v25 offset0:247 offset1:255
	v_lshl_add_u64 v[4:5], v[58:59], 0, v[10:11]
	global_store_dwordx4 v[4:5], v[0:3], off nt
	v_or_b32_e32 v4, s28, v27
	v_lshlrev_b32_e32 v10, 12, v4
	s_waitcnt lgkmcnt(6)
	v_cvt_pk_bf16_f32 v0, v14, v6
	s_waitcnt lgkmcnt(4)
	v_cvt_pk_bf16_f32 v1, v16, v18
	s_waitcnt lgkmcnt(2)
	v_cvt_pk_bf16_f32 v2, v20, v54
	s_waitcnt lgkmcnt(0)
	v_cvt_pk_bf16_f32 v3, v56, v60
	v_lshl_add_u64 v[4:5], v[58:59], 0, v[10:11]
	global_store_dwordx4 v[4:5], v[0:3], off nt
	v_or_b32_e32 v4, s28, v28
	v_lshlrev_b32_e32 v10, 12, v4
	v_cvt_pk_bf16_f32 v0, v15, v7
	v_cvt_pk_bf16_f32 v1, v17, v19
	v_cvt_pk_bf16_f32 v2, v21, v55
	v_cvt_pk_bf16_f32 v3, v57, v61
	v_lshl_add_u64 v[4:5], v[58:59], 0, v[10:11]
	global_store_dwordx4 v[4:5], v[0:3], off nt
	s_waitcnt lgkmcnt(0)
